# item queues: first item per workgroup assigned statically (no atomic), dynamic indices start at 256
# baseline (speedup 1.0000x reference)
.LBB0_13:
	s_mov_b32 s101, 1
	v_readlane_b32 s0, v252, 0
	v_readlane_b32 s8, v252, 3
	s_mov_b32 s70, s0
	v_readlane_b32 s0, v252, 1
	v_readlane_b32 s9, v252, 4
	s_mov_b32 s72, s0
	s_load_dwordx2 s[80:81], s[8:9], 0x140
	v_readlane_b32 s1, v252, 2
	s_mov_b64 s[10:11], -1
	s_mov_b64 s[12:13], 0
	s_cmp_lt_i32 s56, 35
	s_mov_b64 s[0:1], 0
	s_waitcnt lgkmcnt(0)
	s_mov_b64 s[4:5], -1
	s_cbranch_scc1 .LBB0_17
	s_cmp_eq_u32 s56, 35
	s_mov_b64 s[0:1], -1
	s_cbranch_scc0 .LBB0_16
	s_mov_b64 s[0:1], 0

.LBB0_500:
	s_and_saveexec_b64 s[14:15], s[92:93]
	s_cbranch_execz .LBB0_504
	s_cmp_eq_u32 s101, 1
	s_cbranch_scc0 .Lq_dyn1
	s_mov_b32 s101, 0
	v_readlane_b32 s100, v252, 0
	s_nop 3
	s_add_i32 s100, s100, 0xffffff00
	v_mov_b32_e32 v2, s100
	v_mov_b32_e32 v0, 0
	s_branch .Lq_join1
.Lq_dyn1:
	s_mov_b64 s[38:39], exec
	v_mbcnt_lo_u32_b32 v0, s38, 0
	v_mbcnt_hi_u32_b32 v0, s39, v0
	v_cmp_eq_u32_e32 vcc, 0, v0
	s_and_saveexec_b64 s[20:21], vcc
	s_cbranch_execz .LBB0_503
	s_bcnt1_i32_b64 s4, s[38:39]
	v_mov_b32_e32 v2, s4
	global_atomic_add v2, v1, v2, s[0:1] sc0

.Lq_join1:
	s_waitcnt vmcnt(0)
	v_readfirstlane_b32 s4, v2
	s_addk_i32 s4, 0x100
	v_mov_b32_e32 v2, s69
	s_nop 0
	v_add_u32_e32 v0, s4, v0
	ds_write_b32 v2, v0

.LBB0_570:
	s_and_saveexec_b64 s[0:1], s[92:93]
	s_cbranch_execz .LBB0_574
	s_cmp_eq_u32 s101, 1
	s_cbranch_scc0 .Lq_dyn2
	s_mov_b32 s101, 0
	v_readlane_b32 s100, v252, 0
	s_nop 3
	s_add_i32 s100, s100, 0xffffff00
	v_mov_b32_e32 v2, s100
	v_mov_b32_e32 v0, 0
	s_branch .Lq_join2
.Lq_dyn2:
	s_mov_b64 s[20:21], exec
	v_mbcnt_lo_u32_b32 v0, s20, 0
	v_mbcnt_hi_u32_b32 v0, s21, v0
	v_cmp_eq_u32_e32 vcc, 0, v0
	s_and_saveexec_b64 s[14:15], vcc
	s_cbranch_execz .LBB0_573
	s_bcnt1_i32_b64 s3, s[20:21]
	v_readlane_b32 s4, v254, 59
	v_mov_b32_e32 v2, s3
	v_readlane_b32 s5, v254, 60
	s_nop 4
	global_atomic_add v2, v1, v2, s[4:5] sc0

.Lq_join2:
	s_waitcnt vmcnt(0)
	v_readfirstlane_b32 s3, v2
	s_addk_i32 s3, 0x100
	v_mov_b32_e32 v2, s69
	s_nop 0
	v_add_u32_e32 v0, s3, v0
	ds_write_b32 v2, v0

.Lq_dyn3:
	s_mov_b64 s[24:25], exec
	v_mbcnt_lo_u32_b32 v0, s24, 0
	v_mbcnt_hi_u32_b32 v0, s25, v0
	v_cmp_eq_u32_e32 vcc, 0, v0
	s_and_saveexec_b64 s[20:21], vcc
	s_cbranch_execz .LBB0_664
	s_bcnt1_i32_b64 s3, s[24:25]
	v_mov_b32_e32 v2, s3
	global_atomic_add v2, v1, v2, s[0:1] sc0

.LBB0_1086:
	s_and_saveexec_b64 s[10:11], s[92:93]
	s_cbranch_execz .LBB0_1090
	s_cmp_eq_u32 s101, 1
	s_cbranch_scc0 .Lq_dyn4
	s_mov_b32 s101, 0
	v_readlane_b32 s100, v252, 0
	s_nop 3
	s_add_i32 s100, s100, 0xffffff00
	v_mov_b32_e32 v2, s100
	v_mov_b32_e32 v0, 0
	s_branch .Lq_join4
.Lq_dyn4:
	s_mov_b64 s[16:17], exec
	v_mbcnt_lo_u32_b32 v0, s16, 0
	v_mbcnt_hi_u32_b32 v0, s17, v0
	v_cmp_eq_u32_e32 vcc, 0, v0
	s_and_saveexec_b64 s[14:15], vcc
	s_cbranch_execz .LBB0_1089
	s_bcnt1_i32_b64 s3, s[16:17]
	v_mov_b32_e32 v2, s3
	global_atomic_add v2, v1, v2, s[0:1] sc0

.Lq_join4:
	s_mov_b64 s[12:13], src_shared_base
	s_waitcnt vmcnt(0)
	v_readfirstlane_b32 s3, v2
	s_addk_i32 s3, 0x100
	s_cmp_lg_u32 s69, -1
	s_cselect_b32 s12, s13, 0
	v_add_u32_e32 v0, s3, v0
	s_cselect_b32 s3, s69, 0
	v_mov_b32_e32 v2, s3
	v_mov_b32_e32 v3, s12
	flat_store_dword v[2:3], v0 sc0 sc1
	s_waitcnt vmcnt(0)
